# attention loop: dropped the 24 'next = current' register copies (only kept values defined on the exit trip)
# baseline (speedup 1.0000x reference)
.LBB0_297:
	s_or_b64 exec, exec, s[2:3]
	v_and_b32_e32 v6, 64, v210
	v_xor_b32_e32 v5, 32, v210
	v_add_u32_e32 v6, 64, v6
	v_cmp_lt_i32_e32 vcc, v5, v6
	v_lshlrev_b32_e32 v125, 2, v4
	v_cmp_lt_u32_e64 s[38:39], v125, v137
	v_cndmask_b32_e32 v5, v210, v5, vcc
	v_lshlrev_b32_e32 v139, 2, v5
	v_cmp_eq_u32_e32 vcc, 0, v4
	s_waitcnt vmcnt(0)
	v_mfma_f32_32x32x16_bf16 v[0:15], v[0:3], v[48:51], 0
	v_mfma_f32_32x32x16_bf16 v[0:15], v[28:31], v[52:55], v[0:15]
	v_mfma_f32_32x32x16_bf16 v[0:15], v[20:23], v[56:59], v[0:15]
	v_mfma_f32_32x32x16_bf16 v[0:15], v[24:27], v[60:63], v[0:15]
	s_nop 11
	v_mul_f32_e32 v0, 0x3e38aa3b, v0
	v_min_f32_e32 v0, 0x42700000, v0
	v_exp_f32_e32 v20, v0
	s_nop 0
	v_add_f32_e32 v20, 1.0, v20
	v_log_f32_e32 v21, v20
	s_nop 0
	v_sub_f32_e32 v0, v0, v21
	v_cndmask_b32_e64 v20, v217, v0, s[38:39]
	v_mul_f32_e32 v0, 0x3e38aa3b, v1
	v_min_f32_e32 v0, 0x42700000, v0
	v_exp_f32_e32 v1, v0
	v_cndmask_b32_e64 v23, 0, v21, s[38:39]
	v_or_b32_e32 v21, 1, v125
	v_cmp_lt_u32_e64 s[38:39], v21, v137
	v_add_f32_e32 v1, 1.0, v1
	v_log_f32_e32 v1, v1
	s_nop 0
	v_sub_f32_e32 v0, v0, v1
	v_cndmask_b32_e64 v22, v217, v0, s[38:39]
	v_mul_f32_e32 v0, 0x3e38aa3b, v2
	v_min_f32_e32 v0, 0x42700000, v0
	v_cndmask_b32_e64 v21, 0, v1, s[38:39]
	v_exp_f32_e32 v1, v0
	v_or_b32_e32 v2, 2, v125
	v_cmp_lt_u32_e64 s[38:39], v2, v137
	v_or_b32_e32 v2, 3, v125
	v_add_f32_e32 v1, 1.0, v1
	v_log_f32_e32 v1, v1
	s_nop 0
	v_sub_f32_e32 v0, v0, v1
	v_cndmask_b32_e64 v25, v217, v0, s[38:39]
	v_mul_f32_e32 v0, 0x3e38aa3b, v3
	v_min_f32_e32 v0, 0x42700000, v0
	v_cndmask_b32_e64 v24, 0, v1, s[38:39]
	v_exp_f32_e32 v1, v0
	v_cmp_lt_u32_e64 s[38:39], v2, v137
	v_or_b32_e32 v2, 8, v125
	v_or_b32_e32 v3, 9, v125
	v_add_f32_e32 v1, 1.0, v1
	v_log_f32_e32 v1, v1
	s_nop 0
	v_sub_f32_e32 v0, v0, v1
	v_cndmask_b32_e64 v27, v217, v0, s[38:39]
	v_mul_f32_e32 v0, 0x3e38aa3b, v4
	v_min_f32_e32 v0, 0x42700000, v0
	v_cndmask_b32_e64 v26, 0, v1, s[38:39]
	v_exp_f32_e32 v1, v0
	v_cmp_lt_u32_e64 s[38:39], v2, v137
	v_or_b32_e32 v4, 10, v125
	v_add_f32_e32 v1, 1.0, v1
	v_log_f32_e32 v1, v1
	s_nop 0
	v_sub_f32_e32 v0, v0, v1
	v_cndmask_b32_e64 v28, v217, v0, s[38:39]
	v_mul_f32_e32 v0, 0x3e38aa3b, v5
	v_min_f32_e32 v0, 0x42700000, v0
	v_cndmask_b32_e64 v2, 0, v1, s[38:39]
	v_exp_f32_e32 v1, v0
	v_cmp_lt_u32_e64 s[38:39], v3, v137
	v_or_b32_e32 v5, 18, v125
	v_add_f32_e32 v1, 1.0, v1
	v_log_f32_e32 v1, v1
	s_nop 0
	v_sub_f32_e32 v0, v0, v1
	v_cndmask_b32_e64 v29, v217, v0, s[38:39]
	v_cndmask_b32_e64 v0, 0, v1, s[38:39]
	v_mul_f32_e32 v1, 0x3e38aa3b, v6
	v_min_f32_e32 v1, 0x42700000, v1
	v_exp_f32_e32 v3, v1
	v_cmp_lt_u32_e64 s[38:39], v4, v137
	v_or_b32_e32 v4, 11, v125
	v_add_f32_e32 v3, 1.0, v3
	v_log_f32_e32 v3, v3
	s_nop 0
	v_sub_f32_e32 v1, v1, v3
	v_cndmask_b32_e64 v31, v217, v1, s[38:39]
	v_mul_f32_e32 v1, 0x3e38aa3b, v7
	v_min_f32_e32 v1, 0x42700000, v1
	v_cndmask_b32_e64 v30, 0, v3, s[38:39]
	v_exp_f32_e32 v3, v1
	v_cmp_lt_u32_e64 s[38:39], v4, v137
	v_or_b32_e32 v4, 16, v125
	v_or_b32_e32 v7, 25, v125
	v_add_f32_e32 v3, 1.0, v3
	v_log_f32_e32 v3, v3
	s_nop 0
	v_sub_f32_e32 v1, v1, v3
	v_cndmask_b32_e64 v96, v217, v1, s[38:39]
	v_mul_f32_e32 v1, 0x3e38aa3b, v8
	v_min_f32_e32 v1, 0x42700000, v1
	v_cndmask_b32_e64 v97, 0, v3, s[38:39]
	v_exp_f32_e32 v3, v1
	v_cmp_lt_u32_e64 s[38:39], v4, v137
	v_or_b32_e32 v4, 17, v125
	v_add_f32_e32 v8, v30, v97
	v_add_f32_e32 v3, 1.0, v3
	v_log_f32_e32 v3, v3
	s_nop 0
	v_sub_f32_e32 v1, v1, v3
	v_cndmask_b32_e64 v98, v217, v1, s[38:39]
	v_mul_f32_e32 v1, 0x3e38aa3b, v9
	v_min_f32_e32 v1, 0x42700000, v1
	v_cndmask_b32_e64 v6, 0, v3, s[38:39]
	v_exp_f32_e32 v3, v1
	v_cmp_lt_u32_e64 s[38:39], v4, v137
	v_add_f32_e32 v3, 1.0, v3
	v_log_f32_e32 v3, v3
	s_nop 0
	v_sub_f32_e32 v1, v1, v3
	v_cndmask_b32_e64 v99, v217, v1, s[38:39]
	v_mul_f32_e32 v1, 0x3e38aa3b, v10
	v_min_f32_e32 v1, 0x42700000, v1
	v_cndmask_b32_e64 v4, 0, v3, s[38:39]
	v_exp_f32_e32 v3, v1
	v_cmp_lt_u32_e64 s[38:39], v5, v137
	v_or_b32_e32 v5, 19, v125
	v_add_f32_e32 v3, 1.0, v3
	v_log_f32_e32 v3, v3
	s_nop 0
	v_sub_f32_e32 v1, v1, v3
	v_cndmask_b32_e64 v100, v217, v1, s[38:39]
	v_mul_f32_e32 v1, 0x3e38aa3b, v11
	v_min_f32_e32 v1, 0x42700000, v1
	v_cndmask_b32_e64 v101, 0, v3, s[38:39]
	v_exp_f32_e32 v3, v1
	v_cmp_lt_u32_e64 s[38:39], v5, v137
	v_or_b32_e32 v5, 24, v125
	v_add_f32_e32 v3, 1.0, v3
	v_log_f32_e32 v3, v3
	s_nop 0
	v_sub_f32_e32 v1, v1, v3
	v_cndmask_b32_e64 v102, v217, v1, s[38:39]
	v_mul_f32_e32 v1, 0x3e38aa3b, v12
	v_min_f32_e32 v1, 0x42700000, v1
	v_cndmask_b32_e64 v103, 0, v3, s[38:39]
	v_exp_f32_e32 v3, v1
	v_cmp_lt_u32_e64 s[38:39], v5, v137
	v_add_f32_e32 v10, v101, v103
	v_add_f32_e32 v3, 1.0, v3
	v_log_f32_e32 v3, v3
	s_nop 0
	v_sub_f32_e32 v1, v1, v3
	v_cndmask_b32_e64 v12, v217, v1, s[38:39]
	v_cndmask_b32_e64 v1, 0, v3, s[38:39]
	v_mul_f32_e32 v3, 0x3e38aa3b, v13
	v_min_f32_e32 v3, 0x42700000, v3
	v_exp_f32_e32 v5, v3
	v_cmp_lt_u32_e64 s[38:39], v7, v137
	v_or_b32_e32 v7, 26, v125
	v_add_f32_e32 v5, 1.0, v5
	v_log_f32_e32 v5, v5
	s_nop 0
	v_sub_f32_e32 v3, v3, v5
	v_cndmask_b32_e64 v13, v217, v3, s[38:39]
	v_mul_f32_e32 v3, 0x3e38aa3b, v14
	v_min_f32_e32 v3, 0x42700000, v3
	v_cndmask_b32_e64 v104, 0, v5, s[38:39]
	v_exp_f32_e32 v5, v3
	v_cmp_lt_u32_e64 s[38:39], v7, v137
	v_or_b32_e32 v7, 27, v125
	v_add_f32_e32 v5, 1.0, v5
	v_log_f32_e32 v5, v5
	s_nop 0
	v_sub_f32_e32 v3, v3, v5
	v_cndmask_b32_e64 v14, v217, v3, s[38:39]
	v_mul_f32_e32 v3, 0x3e38aa3b, v15
	v_min_f32_e32 v3, 0x42700000, v3
	v_cndmask_b32_e64 v105, 0, v5, s[38:39]
	v_exp_f32_e32 v5, v3
	v_cmp_lt_u32_e64 s[38:39], v7, v137
	v_add_f32_e32 v7, v1, v104
	v_add_f32_e32 v5, 1.0, v5
	v_log_f32_e32 v5, v5
	s_nop 0
	v_sub_f32_e32 v3, v3, v5
	v_cndmask_b32_e64 v15, v217, v3, s[38:39]
	v_cndmask_b32_e64 v106, 0, v5, s[38:39]
	v_add_f32_e32 v3, v23, v21
	v_add_f32_e32 v5, v24, v26
	v_add_f32_e32 v93, v3, v5
	v_add_f32_e32 v5, v105, v106
	v_pk_add_f32 v[6:7], v[6:7], v[4:5]
	ds_bpermute_b32 v11, v139, v7
	ds_bpermute_b32 v94, v139, v93
	s_waitcnt lgkmcnt(1)
	v_pk_add_f32 v[6:7], v[6:7], v[10:11]
	ds_bpermute_b32 v9, v139, v6
	v_mov_b32_e32 v3, v6
	v_mov_b32_e32 v1, v7
	v_pk_add_f32 v[2:3], v[2:3], v[0:1]
	s_waitcnt lgkmcnt(0)
	v_pk_add_f32 v[2:3], v[2:3], v[8:9]
	ds_bpermute_b32 v1, v139, v2
	v_add_f32_e32 v2, v2, v3
	s_waitcnt lgkmcnt(0)
	v_add_f32_e32 v95, v2, v1
	v_cndmask_b32_e32 v1, 0, v1, vcc
	v_add_f32_e32 v1, v1, v3
	v_cndmask_b32_e32 v2, 0, v94, vcc
	v_add_f32_e32 v1, 0, v1
	v_add_f32_e32 v2, v2, v95
	v_sub_f32_e32 v3, v96, v1
	v_add_f32_e32 v1, v97, v1
	v_add_f32_e32 v2, 0, v2
	v_sub_f32_e32 v10, v31, v1
	v_add_f32_e32 v1, v30, v1
	v_sub_f32_e32 v5, v27, v2
	v_add_f32_e32 v2, v26, v2
	v_add_f32_e32 v0, v0, v1
	v_sub_f32_e32 v6, v25, v2
	v_add_f32_e32 v2, v24, v2
	v_sub_f32_e32 v0, v28, v0
	v_sub_f32_e32 v8, v22, v2
	v_add_f32_e32 v2, v21, v2
	v_exp_f32_e32 v21, v0
	v_cndmask_b32_e32 v0, 0, v9, vcc
	v_add_f32_e32 v0, v0, v7
	v_add_f32_e32 v0, 0, v0
	v_sub_f32_e32 v2, v20, v2
	v_sub_f32_e32 v20, v29, v1
	v_sub_f32_e32 v1, v102, v0
	v_add_f32_e32 v0, v103, v0
	v_exp_f32_e32 v96, v1
	v_sub_f32_e32 v1, v100, v0
	v_add_f32_e32 v0, v101, v0
	v_exp_f32_e32 v97, v1
	v_sub_f32_e32 v1, v99, v0
	v_add_f32_e32 v0, v4, v0
	v_sub_f32_e32 v0, v98, v0
	v_exp_f32_e32 v98, v0
	v_add_f32_e32 v0, 0, v11
	v_cndmask_b32_e32 v0, 0, v0, vcc
	v_exp_f32_e32 v5, v5
	v_exp_f32_e32 v6, v6
	v_exp_f32_e32 v8, v8
	v_exp_f32_e32 v2, v2
	v_exp_f32_e32 v3, v3
	v_exp_f32_e32 v10, v10
	v_exp_f32_e32 v20, v20
	v_exp_f32_e32 v99, v1
	v_sub_f32_e32 v1, v15, v0
	v_add_f32_e32 v0, v0, v106
	v_exp_f32_e32 v100, v1
	v_sub_f32_e32 v1, v14, v0
	v_add_f32_e32 v0, v105, v0
	v_exp_f32_e32 v101, v1
	v_sub_f32_e32 v1, v13, v0
	v_add_f32_e32 v0, v104, v0
	v_sub_f32_e32 v0, v12, v0
	v_exp_f32_e32 v102, v1
	v_exp_f32_e32 v103, v0
	v_cvt_pk_bf16_f32 v0, v2, v8
	v_cvt_pk_bf16_f32 v1, v6, v5
	v_cvt_pk_bf16_f32 v2, v21, v20
	v_cvt_pk_bf16_f32 v3, v10, v3
	s_nop 1
	v_mfma_f32_32x32x16_bf16 v[16:31], v[16:19], v[0:3], 0
	v_mfma_f32_32x32x16_bf16 v[0:15], v[44:47], v[0:3], 0
	v_cvt_pk_bf16_f32 v44, v98, v99
	v_cvt_pk_bf16_f32 v45, v97, v96
	v_cvt_pk_bf16_f32 v46, v103, v102
	v_cvt_pk_bf16_f32 v47, v101, v100
	s_nop 1
	v_mfma_f32_32x32x16_bf16 v[16:31], v[36:39], v[44:47], v[16:31]
	v_mfma_f32_32x32x16_bf16 v[0:15], v[40:43], v[44:47], v[0:15]
	s_and_saveexec_b64 s[4:5], s[36:37]
	s_cbranch_execz .LBB0_188
	v_add_f32_e32 v36, v93, v95
	v_add_f32_e32 v36, v36, v94
	s_mov_b32 s2, 0x43170000
	v_cmp_lt_f32_e64 s[36:37], s2, v36
	s_cmp_eq_u64 s[36:37], exec
	s_cbranch_scc1 .LBB0_188
	v_lshrrev_b32_e32 v37, 6, v92
	v_add_f32_e32 v140, 0, v36
	v_add_u16_e32 v36, s9, v37
	v_and_b32_e32 v36, 0xff, v36
	v_not_b32_e32 v37, 63
	v_lshl_add_u32 v176, v36, 5, v37
	s_mov_b64 s[38:39], 0
	s_branch .LBB0_301

.LBB0_301:
	v_cmp_lt_i32_e64 s[36:37], 1, v138
	s_and_saveexec_b64 s[2:3], s[36:37]
	s_cbranch_execz .LBB0_303
	v_add_u32_e32 v36, v137, v176
	v_mad_u64_u32 v[36:37], s[6:7], v36, s13, v[128:129]
	global_load_dwordx4 v[104:107], v[36:37], off offset:512
	global_load_dwordx4 v[100:103], v[36:37], off offset:544
	global_load_dwordx4 v[96:99], v[36:37], off offset:576
	global_load_dwordx4 v[92:95], v[36:37], off offset:608
	v_lshl_add_u64 v[36:37], v[176:177], 1, v[132:133]
	v_mov_b32_e32 v135, v177
	v_mov_b32_e32 v131, v177
	v_lshl_add_u64 v[38:39], v[36:37], 0, v[134:135]
	v_lshl_add_u64 v[36:37], v[36:37], 0, v[130:131]
	global_load_dwordx4 v[108:111], v[38:39], off offset:16
	global_load_dwordx4 v[116:119], v[38:39], off
	global_load_dwordx4 v[112:115], v[36:37], off offset:16
	global_load_dwordx4 v[120:123], v[36:37], off
